# attention tile loop: back-edge rotation (barrier at loop head, next-tile LDS read bases and pointer advances computed before the barrier)
# speedup vs baseline: 1.0007x; 1.0007x over previous
.LBB0_173:
	s_or_b64 exec, exec, s[6:7]
	s_add_i32 s6, s34, 1
	s_waitcnt vmcnt(1)
	v_add_u32_e32 v24, 0, v116
	s_add_u32 s34, s21, s35
	v_mov_b32_e32 v26, v157
	v_mov_b32_e32 v27, v157
	s_waitcnt vmcnt(0)
	ds_write_b128 v24, v[28:31] offset:14336
	s_addc_u32 s35, s10, 0
	v_mov_b32_e32 v24, v157
	v_mov_b32_e32 v25, v157
	v_mov_b64_e32 v[30:31], v[26:27]
	v_mov_b64_e32 v[34:35], v[26:27]
	v_mov_b64_e32 v[38:39], v[26:27]
	v_mov_b64_e32 v[42:43], v[26:27]
	v_mov_b64_e32 v[46:47], v[26:27]
	v_mov_b64_e32 v[50:51], v[26:27]
	v_mov_b64_e32 v[54:55], v[26:27]
	v_mov_b64_e32 v[58:59], v[26:27]
	v_mov_b64_e32 v[62:63], v[26:27]
	v_lshl_add_u64 v[132:133], v[120:121], 0, s[34:35]
	v_lshl_add_u64 v[134:135], v[122:123], 0, s[2:3]
	v_lshl_add_u64 v[136:137], v[124:125], 0, s[2:3]
	s_mov_b32 s7, 0
	v_mov_b32_e32 v128, 0xf149f2ca
	v_mov_b64_e32 v[28:29], v[24:25]
	v_mov_b64_e32 v[32:33], v[24:25]
	v_mov_b64_e32 v[36:37], v[24:25]
	v_mov_b64_e32 v[40:41], v[24:25]
	v_mov_b64_e32 v[44:45], v[24:25]
	v_mov_b64_e32 v[48:49], v[24:25]
	v_mov_b64_e32 v[52:53], v[24:25]
	v_mov_b64_e32 v[56:57], v[24:25]
	v_mov_b64_e32 v[60:61], v[24:25]
	v_mov_b32_e32 v130, 0xf149f2ca
	s_waitcnt lgkmcnt(0)
	v_mov_b32_e32 v250, s52
	v_mov_b32_e32 v251, s52
	v_mov_b32_e32 v252, s52
	v_mov_b32_e32 v253, s52
	v_readfirstlane_b32 s2, v160
	s_cmpk_ge_u32 s2, 0x100
	s_cbranch_scc0 .Lattn_noprio
	s_setprio 1
.Lattn_noprio:
	v_add_u32_e32 v104, v110, v142
	v_add_u32_e32 v147, v138, v143
	s_branch .LBB0_175
.LBB0_175:
	s_barrier
	ds_read_b128 v[162:165], v104
	ds_read_b128 v[166:169], v104 offset:64
	ds_read_b128 v[170:173], v104 offset:128
	ds_read_b128 v[174:177], v104 offset:3584
	ds_read_b128 v[178:181], v104 offset:3648
	ds_read_b128 v[182:185], v104 offset:3712
	ds_read_b128 v[186:189], v104 offset:7168
	ds_read_b128 v[214:217], v104 offset:7232
	ds_read_b128 v[218:221], v104 offset:7296
	ds_read_b128 v[222:225], v104 offset:10752
	ds_read_b128 v[226:229], v104 offset:10816
	ds_read_b128 v[230:233], v104 offset:10880
	global_load_dwordx4 v[72:75], v[136:137], off
	global_load_dwordx4 v[68:71], v[134:135], off
	global_load_dwordx4 v[64:67], v[132:133], off
	s_and_b32 s21, s7, 15
	s_cbranch_scc0 .Lattn_refresh
	s_waitcnt lgkmcnt(11)
	v_mfma_f32_16x16x32_bf16 v[92:95], v[162:165], v[0:3], v[148:151]
	v_mfma_f32_16x16x32_bf16 v[76:79], v[162:165], v[8:11], v[152:155]
	ds_read_b64 v[234:235], v147 offset:14336
	ds_read_b64 v[236:237], v147 offset:14368
	s_waitcnt lgkmcnt(12)
	v_mfma_f32_16x16x32_bf16 v[92:95], v[166:169], v[4:7], v[92:95]
	v_mfma_f32_16x16x32_bf16 v[76:79], v[166:169], v[12:15], v[76:79]
	ds_read_b64 v[238:239], v147 offset:14400
	ds_read_b64 v[240:241], v147 offset:14432
	s_waitcnt lgkmcnt(13)
	v_mfma_f32_16x16x32_bf16 v[92:95], v[170:173], v[16:19], v[92:95]
	v_mfma_f32_16x16x32_bf16 v[76:79], v[170:173], v[20:23], v[76:79]
	ds_read_b64 v[242:243], v147 offset:16640
	ds_read_b64 v[244:245], v147 offset:16672
	s_waitcnt lgkmcnt(14)
	v_mfma_f32_16x16x32_bf16 v[96:99], v[174:177], v[0:3], v[148:151]
	v_mfma_f32_16x16x32_bf16 v[80:83], v[174:177], v[8:11], v[152:155]
	ds_read_b64 v[246:247], v147 offset:16704
	s_waitcnt lgkmcnt(14)
	v_mfma_f32_16x16x32_bf16 v[96:99], v[178:181], v[4:7], v[96:99]
	v_mfma_f32_16x16x32_bf16 v[80:83], v[178:181], v[12:15], v[80:83]
	ds_read_b64 v[248:249], v147 offset:16736
	s_waitcnt lgkmcnt(14)
	v_mfma_f32_16x16x32_bf16 v[96:99], v[182:185], v[16:19], v[96:99]
	v_mfma_f32_16x16x32_bf16 v[80:83], v[182:185], v[20:23], v[80:83]
	ds_read_b64 v[162:163], v147 offset:18944
	s_waitcnt lgkmcnt(14)
	v_mfma_f32_16x16x32_bf16 v[100:103], v[186:189], v[0:3], v[148:151]
	v_mfma_f32_16x16x32_bf16 v[84:87], v[186:189], v[8:11], v[152:155]
	ds_read_b64 v[164:165], v147 offset:18976
	s_waitcnt lgkmcnt(14)
	v_mfma_f32_16x16x32_bf16 v[100:103], v[214:217], v[4:7], v[100:103]
	v_mfma_f32_16x16x32_bf16 v[84:87], v[214:217], v[12:15], v[84:87]
	ds_read_b64 v[166:167], v147 offset:19008
	s_waitcnt lgkmcnt(14)
	v_mfma_f32_16x16x32_bf16 v[100:103], v[218:221], v[16:19], v[100:103]
	v_mfma_f32_16x16x32_bf16 v[84:87], v[218:221], v[20:23], v[84:87]
	ds_read_b64 v[168:169], v147 offset:19040
	s_waitcnt lgkmcnt(14)
	v_mfma_f32_16x16x32_bf16 v[104:107], v[222:225], v[0:3], v[148:151]
	v_mfma_f32_16x16x32_bf16 v[88:91], v[222:225], v[8:11], v[152:155]
	ds_read_b64 v[170:171], v147 offset:21248
	s_waitcnt lgkmcnt(14)
	v_mfma_f32_16x16x32_bf16 v[104:107], v[226:229], v[4:7], v[104:107]
	v_mfma_f32_16x16x32_bf16 v[88:91], v[226:229], v[12:15], v[88:91]
	ds_read_b64 v[172:173], v147 offset:21280
	s_waitcnt lgkmcnt(14)
	v_mfma_f32_16x16x32_bf16 v[104:107], v[230:233], v[16:19], v[104:107]
	v_mfma_f32_16x16x32_bf16 v[88:91], v[230:233], v[20:23], v[88:91]
	s_waitcnt lgkmcnt(13)
	ds_read_b64 v[174:175], v147 offset:21312
	ds_read_b64 v[176:177], v147 offset:21344

.Lattn_skipw:
	s_waitcnt lgkmcnt(15)
	v_mfma_f32_16x16x32_bf16 v[60:63], v[234:237], v[92:95], v[60:63]
	v_mfma_f32_16x16x32_bf16 v[56:59], v[234:237], v[76:79], v[56:59]
	s_waitcnt lgkmcnt(14)
	v_mfma_f32_16x16x32_bf16 v[60:63], v[238:241], v[96:99], v[60:63]
	v_mfma_f32_16x16x32_bf16 v[56:59], v[238:241], v[80:83], v[56:59]
	s_waitcnt lgkmcnt(12)
	v_mfma_f32_16x16x32_bf16 v[52:55], v[242:245], v[92:95], v[52:55]
	v_mfma_f32_16x16x32_bf16 v[48:51], v[242:245], v[76:79], v[48:51]
	s_waitcnt lgkmcnt(10)
	v_mfma_f32_16x16x32_bf16 v[52:55], v[246:249], v[96:99], v[52:55]
	v_mfma_f32_16x16x32_bf16 v[48:51], v[246:249], v[80:83], v[48:51]
	s_waitcnt lgkmcnt(8)
	v_mfma_f32_16x16x32_bf16 v[44:47], v[162:165], v[92:95], v[44:47]
	v_mfma_f32_16x16x32_bf16 v[40:43], v[162:165], v[76:79], v[40:43]
	s_waitcnt lgkmcnt(6)
	v_mfma_f32_16x16x32_bf16 v[44:47], v[166:169], v[96:99], v[44:47]
	v_mfma_f32_16x16x32_bf16 v[40:43], v[166:169], v[80:83], v[40:43]
	s_waitcnt lgkmcnt(4)
	v_mfma_f32_16x16x32_bf16 v[36:39], v[170:173], v[92:95], v[36:39]
	v_mfma_f32_16x16x32_bf16 v[32:35], v[170:173], v[76:79], v[32:35]
	s_waitcnt lgkmcnt(2)
	v_mfma_f32_16x16x32_bf16 v[36:39], v[174:177], v[96:99], v[36:39]
	v_mfma_f32_16x16x32_bf16 v[32:35], v[174:177], v[80:83], v[32:35]
	v_mfma_f32_16x16x32_bf16 v[28:31], v[250:253], v[92:95], v[28:31]
	v_mfma_f32_16x16x32_bf16 v[24:27], v[250:253], v[76:79], v[24:27]
	v_mfma_f32_16x16x32_bf16 v[28:31], v[250:253], v[96:99], v[28:31]
	v_mfma_f32_16x16x32_bf16 v[24:27], v[250:253], v[80:83], v[24:27]
	v_add3_u32 v104, s10, v110, v142
	v_add3_u32 v147, s10, v138, v143
	v_lshl_add_u64 v[132:133], v[132:133], 0, s[50:51]
	v_lshl_add_u64 v[134:135], v[134:135], 0, s[4:5]
	v_lshl_add_u64 v[136:137], v[136:137], 0, s[4:5]
	s_cmp_eq_u32 s6, s7
	s_waitcnt lgkmcnt(0)
	s_cbranch_scc0 .LBB0_175
	s_barrier
	s_branch .LBB0_161
